# P0: hand-written w_in transposes with 8 row loads in flight per item
# speedup vs baseline: 1.0061x; 1.0032x over previous
.LBB0_83:
	s_andn2_b64 vcc, exec, s[2:3]
	s_cbranch_vccnz .LBB0_5
	s_mul_hi_i32 s2, s48, 0xd20d20d3
	s_add_i32 s2, s2, s48
	s_lshr_b32 s3, s2, 31
	s_ashr_i32 s4, s2, 8
	s_add_i32 s4, s4, s3
	s_mul_i32 s2, s4, 0x138
	s_sub_i32 s5, s48, s2
	s_lshl_b32 s5, s5, 5
	s_lshl_b32 s16, s4, 6
	s_cmpk_lt_u32 s5, 0x400
	s_cselect_b32 s2, 1, 0
	s_add_i32 s3, s5, 0xfffff600
	s_cmpk_lt_u32 s3, 0x400
	s_cselect_b32 s3, 1, 0
	s_or_b32 s2, s2, s3
	s_cmp_lg_u32 s2, 0
	s_cselect_b32 s2, 0x3e0293ee, 1.0
	v_mov_b32_e32 v4, s2
	v_mul_u32_u24_e32 v6, 0x9880, v212
	v_lshl_add_u32 v6, v195, 2, v6
	v_lshlrev_b32_e32 v7, 2, v195
	v_lshl_add_u32 v7, v212, 12, v7
	v_add_u32_e32 v160, v213, v214
	v_add_u32_e32 v161, 0x420, v160
	v_add_u32_e32 v162, 0x840, v160
	v_add_u32_e32 v163, 0xc60, v160
	v_add_u32_e32 v164, 0x1080, v160
	v_add_u32_e32 v165, 0x14a0, v160
	v_add_u32_e32 v166, 0x18c0, v160
	v_add_u32_e32 v167, 0x1ce0, v160
	s_lshl_b32 s2, s5, 12
	s_lshl_b32 s3, s16, 1
	s_add_i32 s2, s2, s3
	s_add_u32 s42, s12, s2
	s_addc_u32 s43, s13, 0
	s_mov_b32 s17, 0
	s_cmpk_lt_u32 s5, 0xa00
	s_cbranch_scc1 .Lwi_go
	s_mov_b32 s17, 24
	s_cmpk_lt_u32 s5, 0x1600
	s_cbranch_scc1 .Lwi_go
	s_mov_b32 s17, 32
	s_cmpk_lt_u32 s5, 0x2600
	s_cbranch_scc1 .Lwi_go
	s_cmpk_eq_u32 s5, 0x2600
	s_cbranch_scc0 .Lwi_zero
	s_mov_b32 s17, 0xffffe400
	v_cmp_lt_u32_e32 vcc, 23, v195
	v_add_u32_e32 v8, 0x3000, v6
	s_nop 1
	v_cndmask_b32_e32 v6, v6, v8, vcc
	s_branch .Lwi_go
.Lwi_zero:
	v_mov_b32_e32 v82, 0
	v_mov_b32_e32 v83, 0
	v_mov_b32_e32 v84, 0
	v_mov_b32_e32 v85, 0
	v_mov_b32_e32 v86, 0
	v_mov_b32_e32 v87, 0
	v_mov_b32_e32 v88, 0
	v_mov_b32_e32 v89, 0
	v_mov_b32_e32 v90, 0
	v_mov_b32_e32 v91, 0
	v_mov_b32_e32 v92, 0
	v_mov_b32_e32 v93, 0
	v_mov_b32_e32 v94, 0
	v_mov_b32_e32 v95, 0
	v_mov_b32_e32 v96, 0
	v_mov_b32_e32 v97, 0
	v_mov_b32_e32 v98, 0
	v_mov_b32_e32 v99, 0
	v_mov_b32_e32 v100, 0
	v_mov_b32_e32 v101, 0
	v_mov_b32_e32 v102, 0
	v_mov_b32_e32 v103, 0
	v_mov_b32_e32 v104, 0
	v_mov_b32_e32 v105, 0
	v_mov_b32_e32 v106, 0
	v_mov_b32_e32 v107, 0
	v_mov_b32_e32 v108, 0
	v_mov_b32_e32 v109, 0
	v_mov_b32_e32 v110, 0
	v_mov_b32_e32 v111, 0
	v_mov_b32_e32 v112, 0
	v_mov_b32_e32 v113, 0
	s_branch .Lwi_tr
.Lwi_go:
	s_mul_i32 s2, s16, 0x2620
	s_add_i32 s2, s2, s5
	s_add_i32 s2, s2, s17
	s_lshl_b32 s2, s2, 2
	s_add_u32 s40, s56, s2
	s_addc_u32 s41, s57, 0
	global_load_dwordx4 v[82:85], v6, s[40:41]
	s_add_u32 s40, s40, 0x4c400
	s_addc_u32 s41, s41, 0
	global_load_dwordx4 v[86:89], v6, s[40:41]
	s_add_u32 s40, s40, 0x4c400
	s_addc_u32 s41, s41, 0
	global_load_dwordx4 v[90:93], v6, s[40:41]
	s_add_u32 s40, s40, 0x4c400
	s_addc_u32 s41, s41, 0
	global_load_dwordx4 v[94:97], v6, s[40:41]
	s_add_u32 s40, s40, 0x4c400
	s_addc_u32 s41, s41, 0
	global_load_dwordx4 v[98:101], v6, s[40:41]
	s_add_u32 s40, s40, 0x4c400
	s_addc_u32 s41, s41, 0
	global_load_dwordx4 v[102:105], v6, s[40:41]
	s_add_u32 s40, s40, 0x4c400
	s_addc_u32 s41, s41, 0
	global_load_dwordx4 v[106:109], v6, s[40:41]
	s_add_u32 s40, s40, 0x4c400
	s_addc_u32 s41, s41, 0
	global_load_dwordx4 v[110:113], v6, s[40:41]
.Lwi_tr:
	s_waitcnt vmcnt(7)
	v_pk_mul_f32 v[82:83], v[4:5], v[82:83] op_sel_hi:[0,1]
	v_pk_mul_f32 v[84:85], v[4:5], v[84:85] op_sel_hi:[0,1]
	ds_write2_b32 v160, v82, v83 offset1:1
	ds_write2_b32 v160, v84, v85 offset0:2 offset1:3
	s_waitcnt vmcnt(6)
	v_pk_mul_f32 v[86:87], v[4:5], v[86:87] op_sel_hi:[0,1]
	v_pk_mul_f32 v[88:89], v[4:5], v[88:89] op_sel_hi:[0,1]
	ds_write2_b32 v161, v86, v87 offset1:1
	ds_write2_b32 v161, v88, v89 offset0:2 offset1:3
	s_waitcnt vmcnt(5)
	v_pk_mul_f32 v[90:91], v[4:5], v[90:91] op_sel_hi:[0,1]
	v_pk_mul_f32 v[92:93], v[4:5], v[92:93] op_sel_hi:[0,1]
	ds_write2_b32 v162, v90, v91 offset1:1
	ds_write2_b32 v162, v92, v93 offset0:2 offset1:3
	s_waitcnt vmcnt(4)
	v_pk_mul_f32 v[94:95], v[4:5], v[94:95] op_sel_hi:[0,1]
	v_pk_mul_f32 v[96:97], v[4:5], v[96:97] op_sel_hi:[0,1]
	ds_write2_b32 v163, v94, v95 offset1:1
	ds_write2_b32 v163, v96, v97 offset0:2 offset1:3
	s_waitcnt vmcnt(3)
	v_pk_mul_f32 v[98:99], v[4:5], v[98:99] op_sel_hi:[0,1]
	v_pk_mul_f32 v[100:101], v[4:5], v[100:101] op_sel_hi:[0,1]
	ds_write2_b32 v164, v98, v99 offset1:1
	ds_write2_b32 v164, v100, v101 offset0:2 offset1:3
	s_waitcnt vmcnt(2)
	v_pk_mul_f32 v[102:103], v[4:5], v[102:103] op_sel_hi:[0,1]
	v_pk_mul_f32 v[104:105], v[4:5], v[104:105] op_sel_hi:[0,1]
	ds_write2_b32 v165, v102, v103 offset1:1
	ds_write2_b32 v165, v104, v105 offset0:2 offset1:3
	s_waitcnt vmcnt(1)
	v_pk_mul_f32 v[106:107], v[4:5], v[106:107] op_sel_hi:[0,1]
	v_pk_mul_f32 v[108:109], v[4:5], v[108:109] op_sel_hi:[0,1]
	ds_write2_b32 v166, v106, v107 offset1:1
	ds_write2_b32 v166, v108, v109 offset0:2 offset1:3
	s_waitcnt vmcnt(0)
	v_pk_mul_f32 v[110:111], v[4:5], v[110:111] op_sel_hi:[0,1]
	v_pk_mul_f32 v[112:113], v[4:5], v[112:113] op_sel_hi:[0,1]
	ds_write2_b32 v167, v110, v111 offset1:1
	ds_write2_b32 v167, v112, v113 offset0:2 offset1:3
	s_waitcnt lgkmcnt(0)
	ds_read2_b32 v[52:53], v218 offset0:0 offset1:8
	ds_read2_b32 v[54:55], v218 offset0:33 offset1:41
	ds_read2_b32 v[56:57], v218 offset0:66 offset1:74
	ds_read2_b32 v[58:59], v218 offset0:99 offset1:107
	ds_read2_b32 v[60:61], v218 offset0:132 offset1:140
	ds_read2_b32 v[62:63], v218 offset0:165 offset1:173
	ds_read2_b32 v[64:65], v218 offset0:198 offset1:206
	ds_read2_b32 v[66:67], v218 offset0:231 offset1:239
	s_waitcnt lgkmcnt(0)
	v_cvt_pk_bf16_f32 v118, v52, v54
	v_cvt_pk_bf16_f32 v119, v56, v58
	v_cvt_pk_bf16_f32 v120, v60, v62
	v_cvt_pk_bf16_f32 v121, v64, v66
	v_cvt_pk_bf16_f32 v122, v53, v55
	v_cvt_pk_bf16_f32 v123, v57, v59
	v_cvt_pk_bf16_f32 v124, v61, v63
	v_cvt_pk_bf16_f32 v125, v65, v67
	global_store_dwordx4 v7, v[118:121], s[42:43]
	s_add_u32 s42, s42, 0x8000
	s_addc_u32 s43, s43, 0
	global_store_dwordx4 v7, v[122:125], s[42:43]
	s_add_u32 s42, s42, 0x8000
	s_addc_u32 s43, s43, 0
	ds_read2_b32 v[52:53], v218 offset0:16 offset1:24
	ds_read2_b32 v[54:55], v218 offset0:49 offset1:57
	ds_read2_b32 v[56:57], v218 offset0:82 offset1:90
	ds_read2_b32 v[58:59], v218 offset0:115 offset1:123
	ds_read2_b32 v[60:61], v218 offset0:148 offset1:156
	ds_read2_b32 v[62:63], v218 offset0:181 offset1:189
	ds_read2_b32 v[64:65], v218 offset0:214 offset1:222
	ds_read2_b32 v[66:67], v218 offset0:247 offset1:255
	s_waitcnt lgkmcnt(0)
	v_cvt_pk_bf16_f32 v118, v52, v54
	v_cvt_pk_bf16_f32 v119, v56, v58
	v_cvt_pk_bf16_f32 v120, v60, v62
	v_cvt_pk_bf16_f32 v121, v64, v66
	v_cvt_pk_bf16_f32 v122, v53, v55
	v_cvt_pk_bf16_f32 v123, v57, v59
	v_cvt_pk_bf16_f32 v124, v61, v63
	v_cvt_pk_bf16_f32 v125, v65, v67
	global_store_dwordx4 v7, v[118:121], s[42:43]
	s_add_u32 s42, s42, 0x8000
	s_addc_u32 s43, s43, 0
	global_store_dwordx4 v7, v[122:125], s[42:43]
	s_add_u32 s42, s42, 0x8000
	s_addc_u32 s43, s43, 0
	s_branch .LBB0_5
	s_mul_hi_i32 s2, s48, 0xd20d20d3
	s_add_i32 s2, s2, s48
	s_lshr_b32 s3, s2, 31
	s_ashr_i32 s16, s2, 8
	s_add_i32 s16, s16, s3
	s_mul_i32 s2, s16, 0x138
	s_mul_i32 s3, s16, 0xffffd900
	s_sub_i32 s2, s48, s2
	s_add_i32 s6, s18, s3
	v_lshl_or_b32 v196, s2, 5, v195
	v_add_u32_e32 v210, s6, v195
	s_movk_i32 s2, 0x9ff
	v_cmp_lt_i32_e32 vcc, s2, v210
	s_and_saveexec_b64 s[2:3], vcc
	s_cbranch_execz .LBB0_98
	s_cmpk_gt_u32 s6, 0x15ff
	s_mov_b64 s[4:5], -1
	s_cbranch_scc0 .LBB0_95
	s_cmpk_gt_u32 s6, 0x25ff
	s_cbranch_scc0 .LBB0_92
	s_movk_i32 s4, 0x2617
	v_cmp_lt_u32_e32 vcc, s4, v210
	s_and_saveexec_b64 s[4:5], vcc
	s_xor_b64 s[4:5], exec, s[4:5]
	s_cmpk_lt_u32 s6, 0x2620
	v_add_u32_e32 v2, 0xfffff000, v210
	s_cselect_b64 vcc, -1, 0
	v_cndmask_b32_e32 v2, -1, v2, vcc
	s_andn2_saveexec_b64 s[4:5], s[4:5]
	v_add_u32_e32 v2, 0xffffe400, v210
	s_or_b64 exec, exec, s[4:5]
	s_mov_b64 s[4:5], 0
